# static s_setprio 1 for waves 0-3 during GEMM, attention and scan phases; no per-segment setprio in GEMM K-loops
# baseline (speedup 1.0000x reference)
; #define LAS __attribute__((address_space(3)))
; __device__ __forceinline__ void attn_phase(LAS unsigned char* lds, const bf16* qkv, const float* gq, const float* gk, const float* relb, bf16* ao, int tid, int lane, int w) {
;     ...
;     int hprev = -1;
;     f32x4 gqa[4], gqb[4];
; #pragma unroll
;     for (int ks = 0; ks < 4; ++ks) {
;         gqa[ks] = *(const f32x4*)(gq + ks * 32 + g * 8) * *(const f32x4*)(gk + ks * 32 + g * 8) * (0.08838834764831845f * LOG2E);
;         gqb[ks] = *(const f32x4*)(gq + ks * 32 + g * 8 + 4) * *(const f32x4*)(gk + ks * 32 + g * 8 + 4) * (0.08838834764831845f * LOG2E); }
;     for (int unit = blockIdx.x; unit < 2048; unit += gridDim.x) {
;         const int nunit = unit + (int)gridDim.x;
;         const int u = ATT_U(unit), bh = unit & 127, b = bh >> 4, h = bh & 15;
;         const int n0 = 2 * u, nq = n0 + (w >> 2);
;         if (h != hprev) { if (tid < 320) *(LAS float*)(lds + BT + tid * 4) = relb[h * 320 + tid] * LOG2E; hprev = h; }
.LBB0_329:
	v_readlane_b32 s4, v245, 38
	v_readlane_b32 s5, v245, 39
	s_andn2_b64 vcc, exec, s[4:5]
	s_cbranch_vccnz .LBB0_367
	v_lshlrev_b64 v[46:47], 2, v[100:101]
	s_waitcnt lgkmcnt(0)
	v_lshl_add_u64 v[54:55], s[24:25], 0, v[46:47]
	s_waitcnt vmcnt(4)
	v_lshl_add_u64 v[56:57], s[18:19], 0, v[46:47]
	global_load_dwordx4 v[38:41], v[54:55], off offset:384
	global_load_dwordx4 v[42:45], v[54:55], off offset:400
	global_load_dwordx4 v[46:49], v[56:57], off offset:384
	global_load_dwordx4 v[50:53], v[56:57], off offset:400
	s_mov_b32 s4, 0x3e0293ee
	s_add_u32 s44, s16, 0x16400000
	s_addc_u32 s45, s17, 0
	v_lshlrev_b32_e32 v150, 2, v0
	s_ashr_i32 s24, s2, 2
	s_cmp_lg_u32 s24, 0
	s_cbranch_scc1 .Lprio_attn_skip
	s_setprio 1

; #define LAS __attribute__((address_space(3)))
; __device__ __forceinline__ void gla_scan(LAS unsigned char* lds, const bf16* proj, const float* dec, const float* qk0, const float* ssq0, bf16* og, float* hssq, int tid, int lane, int w) {
;     asm volatile("" : "+v"(tid), "+v"(lane)); asm volatile("" : "+s"(w));
;     constexpr int QS = 528, VS = 144, XS = 272;
;     constexpr int QD = 0, KI = 33792, VV = 67584, AB = 76800, XO = 86016, DC = 103424;
;     const int g = lane >> 4, i16 = lane & 15, dvt = w & 3, half = w >> 2;
.LBB0_429:
	s_or_b64 exec, exec, s[16:17]
	s_waitcnt lgkmcnt(0)
	v_mov_b32_e32 v2, v202
	s_barrier
	s_mov_b64 s[16:17], s[72:73]
	v_readfirstlane_b32 s2, v2
	v_and_b32_e32 v0, 63, v2
	s_ashr_i32 s2, s2, 6
	s_cmp_ge_u32 s2, 4
	s_cbranch_scc1 .Lprio_scan_skip
	s_setprio 1
